# v7: v6 + P6 tail w_down int8 items: row scales preloaded one item ahead, counted vmcnt so next-item prefetch overlaps (was vmcnt(0) per 8-row block)
# speedup vs baseline: 1.0216x; 1.0049x over previous
.LBB0_785:
	v_ashrrev_i32_e32 v64, 3, v0
	s_mov_b32 s93, 0
	v_add_u32_e32 v88, s30, v64
	v_ashrrev_i32_e32 v89, 31, v88
	v_lshl_add_u64 v[88:89], v[88:89], 2, s[36:37]
	global_load_dword v80, v[88:89], off
	global_load_dword v81, v[88:89], off offset:32
	global_load_dword v82, v[88:89], off offset:64
	global_load_dword v83, v[88:89], off offset:96
	v_lshlrev_b32_e32 v1, 2, v0
	v_and_b32_e32 v2, 28, v1
	v_add_u32_e32 v1, s38, v64
	v_mad_i64_i32 v[4:5], s[10:11], s8, v1, 0
	v_lshl_add_u64 v[4:5], v[4:5], 2, s[6:7]
	s_ashr_i32 s31, s30, 31
	v_mov_b32_e32 v67, 0
	v_lshl_add_u64 v[4:5], s[30:31], 2, v[4:5]
	v_lshlrev_b32_e32 v66, 2, v2
	s_mov_b32 s29, 0
	v_lshl_add_u64 v[4:5], v[4:5], 0, v[66:67]
	s_lshl_b32 s28, s8, 5
	v_lshl_add_u64 v[6:7], v[4:5], 0, s[28:29]
	global_load_dwordx4 v[60:63], v[4:5], off nt
	global_load_dwordx4 v[56:59], v[6:7], off nt
	v_lshl_add_u64 v[4:5], v[6:7], 0, s[28:29]
	v_lshl_add_u64 v[6:7], v[4:5], 0, s[28:29]
	global_load_dwordx4 v[52:55], v[4:5], off nt
	global_load_dwordx4 v[48:51], v[6:7], off nt
	v_lshl_add_u64 v[4:5], v[6:7], 0, s[28:29]
	v_lshl_add_u64 v[6:7], v[4:5], 0, s[28:29]
	global_load_dwordx4 v[44:47], v[4:5], off nt
	global_load_dwordx4 v[40:43], v[6:7], off nt
	v_lshl_add_u64 v[4:5], v[6:7], 0, s[28:29]
	v_lshl_add_u64 v[6:7], v[4:5], 0, s[28:29]
	global_load_dwordx4 v[36:39], v[4:5], off nt
	global_load_dwordx4 v[32:35], v[6:7], off nt
	s_sub_i32 s12, s64, s2
	s_lshl_b32 s2, s12, 3
	v_readlane_b32 s13, v247, 3
	s_movk_i32 s6, 0x84
	v_and_b32_e32 v4, 7, v0
	v_and_b32_e32 v6, 1, v0
	v_and_b32_e32 v0, 2, v0
	v_add_u32_e32 v1, s13, v66
	v_mul_lo_u32 v3, v64, s6
	v_mul_u32_u24_e32 v5, 0x420, v4
	v_cmp_eq_u32_e64 s[8:9], 0, v0
	v_lshlrev_b32_e32 v0, 2, v64
	s_add_i32 s3, s2, s3
	v_add_u32_e32 v72, 8, v64
	v_add_u32_e32 v73, 16, v64
	v_add_u32_e32 v74, 24, v64
	v_lshlrev_b32_e32 v68, 3, v4
	v_mov_b32_e32 v69, v67
	v_cmp_eq_u32_e64 s[6:7], 0, v6
	v_cmp_eq_u32_e64 s[10:11], 0, v4
	v_add3_u32 v75, s13, v5, v0
	v_ashrrev_i32_e32 v65, 31, v64
	s_lshl_b32 s34, s3, 5
	s_lshl_b32 s35, s12, 8
	v_lshlrev_b32_e32 v66, 2, v2
	v_add_u32_e32 v76, v1, v3
	s_mov_b32 s45, 0x42fe0000
	s_mov_b32 s62, 0xc0c0400
	s_mov_b32 s63, 0x5040100
	v_mov_b32_e32 v77, 0x3e0293ee
	s_mov_b64 s[46:47], s[50:51]
	s_mov_b64 s[48:49], s[36:37]
	s_mov_b32 s67, s71
	s_mov_b32 s65, s72
	s_mov_b32 s70, s39
	s_branch .LBB0_787

.LBB0_787:
	s_cmp_lt_i32 s3, 0x9e00
	s_cselect_b64 s[54:55], -1, 0
	s_cmp_gt_i32 s3, 0x9dff
	s_mov_b32 s73, s38
	s_mov_b32 s52, s30
	v_mov_b32_e32 v78, v70
	s_cbranch_scc1 .LBB0_794
	s_cmpk_gt_i32 s3, 0x47ff
	s_cbranch_scc0 .LBB0_791
	s_add_i32 s12, s3, 0xffffb800
	s_lshr_b32 s12, s12, 1
	s_and_b32 s73, s12, 0x7fffffc0
	s_and_b32 s52, s34, 0xfe0
	s_mov_b64 s[12:13], s[22:23]
	s_mov_b32 s70, 1
	s_cbranch_execz .LBB0_792
	s_mov_b32 s65, 2
	s_mov_b64 s[56:57], 0x1000
	s_movk_i32 s67, 0x2b00
	v_mov_b32_e32 v78, 0x3d000000
	s_mov_b64 s[46:47], s[24:25]
	s_mov_b64 s[48:49], s[26:27]
	v_add_u32_e32 v88, s52, v64
	v_ashrrev_i32_e32 v89, 31, v88
	v_lshl_add_u64 v[88:89], v[88:89], 2, s[48:49]
	global_load_dword v84, v[88:89], off
	global_load_dword v85, v[88:89], off offset:32
	global_load_dword v86, v[88:89], off offset:64
	global_load_dword v87, v[88:89], off offset:96
	s_branch .LBB0_793

.LBB0_793:
	v_add_u32_e32 v0, s73, v64
	v_mad_i64_i32 v[0:1], s[58:59], s56, v0, 0
	v_lshl_add_u64 v[0:1], v[0:1], 2, s[12:13]
	s_ashr_i32 s53, s52, 31
	v_lshl_add_u64 v[0:1], s[52:53], 2, v[0:1]
	v_lshl_add_u64 v[0:1], v[0:1], 0, v[66:67]
	s_lshl_b32 s28, s56, 5
	v_lshl_add_u64 v[8:9], v[0:1], 0, s[28:29]
	global_load_dwordx4 v[4:7], v[0:1], off nt
	s_nop 0
	global_load_dwordx4 v[0:3], v[8:9], off nt
	v_lshl_add_u64 v[8:9], v[8:9], 0, s[28:29]
	v_lshl_add_u64 v[16:17], v[8:9], 0, s[28:29]
	global_load_dwordx4 v[12:15], v[8:9], off nt
	s_nop 0
	global_load_dwordx4 v[8:11], v[16:17], off nt
	v_lshl_add_u64 v[16:17], v[16:17], 0, s[28:29]
	v_lshl_add_u64 v[24:25], v[16:17], 0, s[28:29]
	global_load_dwordx4 v[20:23], v[16:17], off nt
	s_nop 0
	global_load_dwordx4 v[16:19], v[24:25], off nt
	v_lshl_add_u64 v[24:25], v[24:25], 0, s[28:29]
	v_lshl_add_u64 v[26:27], v[24:25], 0, s[28:29]
	global_load_dwordx4 v[28:31], v[24:25], off nt
	s_nop 0
	global_load_dwordx4 v[24:27], v[26:27], off nt
	s_cmp_eq_u32 s93, 0
	s_cbranch_scc1 .Ltl6_first
	s_waitcnt vmcnt(16)
	s_branch .Ltl6_go
.Ltl6_first:
	s_mov_b32 s93, 1
	s_waitcnt vmcnt(12)
	s_branch .Ltl6_go

.Ltl6_go:
	ds_write2_b32 v76, v60, v61 offset1:1
	ds_write2_b32 v76, v62, v63 offset0:2 offset1:3
	v_add_u32_e32 v60, 0x420, v76
	s_nop 0
	ds_write2_b32 v60, v56, v57 offset1:1
	v_add_u32_e32 v56, 0x428, v76
	ds_write2_b32 v56, v58, v59 offset1:1
	v_add_u32_e32 v56, 0x840, v76
	s_nop 0
	ds_write2_b32 v56, v52, v53 offset1:1
	v_add_u32_e32 v52, 0x848, v76
	ds_write2_b32 v52, v54, v55 offset1:1
	v_add_u32_e32 v52, 0xc60, v76
	s_nop 0
	ds_write2_b32 v52, v48, v49 offset1:1
	v_add_u32_e32 v48, 0xc68, v76
	ds_write2_b32 v48, v50, v51 offset1:1
	v_add_u32_e32 v48, 0x1080, v76
	s_nop 0
	ds_write2_b32 v48, v44, v45 offset1:1
	v_add_u32_e32 v44, 0x1088, v76
	ds_write2_b32 v44, v46, v47 offset1:1
	v_add_u32_e32 v44, 0x14a0, v76
	s_nop 0
	ds_write2_b32 v44, v40, v41 offset1:1
	v_add_u32_e32 v40, 0x14a8, v76
	ds_write2_b32 v40, v42, v43 offset1:1
	v_add_u32_e32 v40, 0x18c0, v76
	s_nop 0
	ds_write2_b32 v40, v36, v37 offset1:1
	v_add_u32_e32 v36, 0x18c8, v76
	ds_write2_b32 v36, v38, v39 offset1:1
	v_add_u32_e32 v36, 0x1ce0, v76
	s_waitcnt lgkmcnt(14)
	ds_write2_b32 v36, v32, v33 offset1:1
	v_add_u32_e32 v32, 0x1ce8, v76
	ds_write2_b32 v32, v34, v35 offset1:1
	s_waitcnt lgkmcnt(0)
	ds_read2_b32 v[32:33], v75 offset1:33
	ds_read2_b32 v[36:37], v75 offset0:132 offset1:165
	ds_read2_b32 v[40:41], v75 offset0:66 offset1:99
	ds_read2_b32 v[42:43], v75 offset0:198 offset1:231
	s_cmp_lg_u32 s39, 0
	s_waitcnt lgkmcnt(3)
	v_mov_b32_e32 v34, v32
	s_waitcnt lgkmcnt(2)
	v_mov_b32_e32 v35, v36
	v_mov_b32_e32 v36, v33
	s_waitcnt lgkmcnt(1)
	v_mov_b32_e32 v32, v40
	s_waitcnt lgkmcnt(0)
	v_mov_b32_e32 v33, v42
	v_mov_b32_e32 v42, v41
	v_pk_mul_f32 v[34:35], v[70:71], v[34:35] op_sel_hi:[0,1]
	v_pk_mul_f32 v[38:39], v[70:71], v[36:37] op_sel_hi:[0,1]
	v_pk_mul_f32 v[36:37], v[70:71], v[32:33] op_sel_hi:[0,1]
	s_cselect_b64 s[56:57], -1, 0
	s_cmp_eq_u32 s39, 0
	v_pk_mul_f32 v[40:41], v[70:71], v[42:43] op_sel_hi:[0,1]
	s_cbranch_scc1 .LBB0_796
	v_pk_add_f32 v[32:33], v[34:35], v[38:39] neg_lo:[0,1] neg_hi:[0,1]
	v_pk_add_f32 v[42:43], v[36:37], v[40:41] neg_lo:[0,1] neg_hi:[0,1]
	v_pk_add_f32 v[34:35], v[34:35], v[38:39]
	v_pk_add_f32 v[36:37], v[36:37], v[40:41]
	v_pk_add_f32 v[40:41], v[32:33], v[42:43] neg_lo:[0,1] neg_hi:[0,1]
	v_pk_add_f32 v[38:39], v[34:35], v[36:37] neg_lo:[0,1] neg_hi:[0,1]
	s_nop 0
	v_add_f32_e32 v44, v38, v39
	v_sub_f32_e32 v38, v38, v39
	v_add_f32_e32 v39, v40, v41
	v_sub_f32_e32 v40, v40, v41
	v_cndmask_b32_e64 v41, -v44, v44, s[6:7]
	s_nop 1
	v_add_f32_dpp v44, v44, v41 quad_perm:[1,0,3,2] row_mask:0xf bank_mask:0xf bound_ctrl:1
	v_cndmask_b32_e64 v41, -v39, v39, s[6:7]
	s_nop 1
	v_add_f32_dpp v45, v39, v41 quad_perm:[1,0,3,2] row_mask:0xf bank_mask:0xf bound_ctrl:1
	v_cndmask_b32_e64 v39, -v38, v38, s[6:7]
	v_mov_b32_e32 v41, v42
	v_mov_b32_e32 v42, v37
	v_add_f32_dpp v46, v38, v39 quad_perm:[1,0,3,2] row_mask:0xf bank_mask:0xf bound_ctrl:1
	v_cndmask_b32_e64 v38, -v40, v40, s[6:7]
	v_mov_b32_e32 v39, v32
	v_mov_b32_e32 v32, v35
	v_add_f32_dpp v47, v40, v38 quad_perm:[1,0,3,2] row_mask:0xf bank_mask:0xf bound_ctrl:1
	v_mov_b32_e32 v38, v34
	v_mov_b32_e32 v40, v36
	v_pk_add_f32 v[38:39], v[38:39], v[40:41]
	v_pk_add_f32 v[32:33], v[32:33], v[42:43]
	v_mov_b32_e32 v36, v67
	v_pk_add_f32 v[34:35], v[38:39], v[32:33] neg_lo:[0,1] neg_hi:[0,1]
	v_pk_add_f32 v[32:33], v[38:39], v[32:33]
	v_mov_b32_e32 v37, v67
	s_nop 0
	v_mov_b32_dpp v36, v32 quad_perm:[1,0,3,2] row_mask:0xf bank_mask:0xf
	v_mov_b32_dpp v37, v33 quad_perm:[1,0,3,2] row_mask:0xf bank_mask:0xf
	v_cndmask_b32_e64 v33, -v33, v33, s[6:7]
	v_cndmask_b32_e64 v32, -v32, v32, s[6:7]
	v_pk_add_f32 v[32:33], v[32:33], v[36:37]
	v_cndmask_b32_e64 v36, -v34, v34, s[6:7]
	s_nop 1
	v_add_f32_dpp v37, v34, v36 quad_perm:[1,0,3,2] row_mask:0xf bank_mask:0xf bound_ctrl:1
	v_cndmask_b32_e64 v34, -v35, v35, s[6:7]
	s_nop 1
	v_add_f32_dpp v38, v35, v34 quad_perm:[1,0,3,2] row_mask:0xf bank_mask:0xf bound_ctrl:1
	v_mov_b32_e32 v34, v67
	v_mov_b32_e32 v35, v67
	s_nop 0
	v_mov_b32_dpp v34, v32 quad_perm:[2,3,0,1] row_mask:0xf bank_mask:0xf
	v_mov_b32_dpp v35, v33 quad_perm:[2,3,0,1] row_mask:0xf bank_mask:0xf
	v_cndmask_b32_e64 v33, -v33, v33, s[8:9]
	v_cndmask_b32_e64 v32, -v32, v32, s[8:9]
	v_pk_add_f32 v[34:35], v[32:33], v[34:35]
	v_cndmask_b32_e64 v32, -v44, v44, s[8:9]
	v_cndmask_b32_e64 v33, -v38, v38, s[8:9]
	s_nop 0
	v_add_f32_dpp v36, v44, v32 quad_perm:[2,3,0,1] row_mask:0xf bank_mask:0xf bound_ctrl:1
	v_cndmask_b32_e64 v32, -v45, v45, s[8:9]
	v_add_f32_dpp v39, v38, v33 quad_perm:[2,3,0,1] row_mask:0xf bank_mask:0xf bound_ctrl:1
	v_cndmask_b32_e64 v33, -v46, v46, s[8:9]
	v_add_f32_dpp v40, v45, v32 quad_perm:[2,3,0,1] row_mask:0xf bank_mask:0xf bound_ctrl:1
	v_cndmask_b32_e64 v32, -v37, v37, s[8:9]
	v_mov_b32_e32 v38, v35
	s_nop 0
	v_add_f32_dpp v32, v37, v32 quad_perm:[2,3,0,1] row_mask:0xf bank_mask:0xf bound_ctrl:1
	v_add_f32_dpp v37, v46, v33 quad_perm:[2,3,0,1] row_mask:0xf bank_mask:0xf bound_ctrl:1
	v_cndmask_b32_e64 v33, -v47, v47, s[8:9]
	v_mov_b32_e32 v35, v32
	s_nop 0
	v_add_f32_dpp v41, v47, v33 quad_perm:[2,3,0,1] row_mask:0xf bank_mask:0xf bound_ctrl:1

.LBB0_800:
	s_cmp_eq_u32 s72, 2
	s_mov_b64 s[58:59], -1
	s_cbranch_scc0 .LBB0_802
	v_add_u32_e32 v32, s30, v64
	v_ashrrev_i32_e32 v33, 31, v32
	v_lshl_add_u64 v[42:43], v[32:33], 2, s[36:37]
	s_nop 0
	v_mov_b64_e32 v[42:43], s[50:51]
	v_mad_u64_u32 v[42:43], s[58:59], v32, s71, v[42:43]
	v_mov_b32_e32 v32, v43
	v_mad_u64_u32 v[32:33], s[58:59], v33, s71, v[32:33]
	s_ashr_i32 s39, s38, 31
	v_mov_b32_e32 v43, v32
	v_lshl_add_u64 v[32:33], v[42:43], 0, s[38:39]
	v_lshl_add_u64 v[32:33], v[32:33], 0, v[68:69]
	s_nop 0
	v_div_scale_f32 v42, s[58:59], v80, v80, s45
	v_rcp_f32_e32 v43, v42
	v_div_scale_f32 v45, vcc, s45, v80, s45
	s_mov_b64 s[58:59], 0
	v_fma_f32 v46, -v42, v43, 1.0
	v_fmac_f32_e32 v43, v46, v43
	v_mul_f32_e32 v46, v45, v43
	v_fma_f32 v47, -v42, v46, v45
	v_fmac_f32_e32 v46, v47, v43
	v_fma_f32 v42, -v42, v46, v45
	v_div_fmas_f32 v42, v42, v43, v46
	v_div_fixup_f32 v42, v42, v80, s45
	v_cmp_lt_f32_e32 vcc, 0, v80
	s_nop 1
	v_cndmask_b32_e32 v42, 0, v42, vcc
	v_fmaak_f32 v43, v40, v42, 0x4b400000
	v_fmaak_f32 v44, v36, v42, 0x4b400000
	v_fmaak_f32 v45, v38, v42, 0x4b400000
	v_fmaak_f32 v46, v34, v42, 0x4b400000
	v_fmaak_f32 v47, v41, v42, 0x4b400000
	v_fmaak_f32 v48, v37, v42, 0x4b400000
	v_fmaak_f32 v49, v39, v42, 0x4b400000
	v_fmaak_f32 v42, v35, v42, 0x4b400000
	v_perm_b32 v43, v43, v44, s62
	v_perm_b32 v44, v45, v46, s62
	v_perm_b32 v45, v47, v48, s62
	v_perm_b32 v46, v49, v42, s62
	v_perm_b32 v42, v43, v44, s63
	v_perm_b32 v43, v45, v46, s63
	global_store_dwordx2 v[32:33], v[42:43], off

.LBB0_814:
	s_cmp_eq_u32 s72, 2
	s_mov_b64 s[58:59], -1
	s_cbranch_scc0 .LBB0_816
	s_ashr_i32 s31, s30, 31
	v_lshl_add_u64 v[42:43], s[30:31], 0, v[64:65]
	v_lshl_add_u64 v[42:43], v[42:43], 2, s[36:37]
	s_nop 0
	v_add_u32_e32 v44, s30, v72
	v_mov_b64_e32 v[42:43], s[50:51]
	v_mad_u64_u32 v[42:43], s[58:59], v44, s71, v[42:43]
	v_ashrrev_i32_e32 v45, 31, v44
	v_mov_b32_e32 v44, v43
	v_mad_u64_u32 v[44:45], s[58:59], v45, s71, v[44:45]
	v_mov_b32_e32 v43, v44
	s_ashr_i32 s39, s38, 31
	v_lshl_add_u64 v[42:43], v[42:43], 0, s[38:39]
	v_lshl_add_u64 v[42:43], v[42:43], 0, v[68:69]
	s_nop 0
	v_div_scale_f32 v44, s[58:59], v81, v81, s45
	v_rcp_f32_e32 v45, v44
	v_div_scale_f32 v46, vcc, s45, v81, s45
	s_mov_b64 s[58:59], 0
	v_fma_f32 v47, -v44, v45, 1.0
	v_fmac_f32_e32 v45, v47, v45
	v_mul_f32_e32 v47, v46, v45
	v_fma_f32 v48, -v44, v47, v46
	v_fmac_f32_e32 v47, v48, v45
	v_fma_f32 v44, -v44, v47, v46
	v_div_fmas_f32 v44, v44, v45, v47
	v_div_fixup_f32 v44, v44, v81, s45
	v_cmp_lt_f32_e32 vcc, 0, v81
	s_nop 1
	v_cndmask_b32_e32 v33, 0, v44, vcc
	v_fmaak_f32 v44, v40, v33, 0x4b400000
	v_fmaak_f32 v45, v36, v33, 0x4b400000
	v_fmaak_f32 v46, v38, v33, 0x4b400000
	v_fmaak_f32 v47, v34, v33, 0x4b400000
	v_fmaak_f32 v48, v41, v33, 0x4b400000
	v_fmaak_f32 v49, v37, v33, 0x4b400000
	v_fmaak_f32 v50, v39, v33, 0x4b400000
	v_fmaak_f32 v33, v35, v33, 0x4b400000
	v_perm_b32 v44, v44, v45, s62
	v_perm_b32 v45, v46, v47, s62
	v_perm_b32 v46, v48, v49, s62
	v_perm_b32 v33, v50, v33, s62
	v_perm_b32 v44, v44, v45, s63
	v_perm_b32 v45, v46, v33, s63
	global_store_dwordx2 v[42:43], v[44:45], off

.LBB0_828:
	s_cmp_eq_u32 s72, 2
	s_mov_b64 s[58:59], -1
	s_cbranch_scc0 .LBB0_830
	s_ashr_i32 s31, s30, 31
	v_lshl_add_u64 v[42:43], s[30:31], 0, v[64:65]
	v_lshl_add_u64 v[42:43], v[42:43], 2, s[36:37]
	s_nop 0
	v_add_u32_e32 v44, s30, v73
	v_mov_b64_e32 v[42:43], s[50:51]
	v_mad_u64_u32 v[42:43], s[58:59], v44, s71, v[42:43]
	v_ashrrev_i32_e32 v45, 31, v44
	v_mov_b32_e32 v44, v43
	v_mad_u64_u32 v[44:45], s[58:59], v45, s71, v[44:45]
	v_mov_b32_e32 v43, v44
	s_ashr_i32 s39, s38, 31
	v_lshl_add_u64 v[42:43], v[42:43], 0, s[38:39]
	v_lshl_add_u64 v[42:43], v[42:43], 0, v[68:69]
	s_nop 0
	v_div_scale_f32 v44, s[58:59], v82, v82, s45
	v_rcp_f32_e32 v45, v44
	v_div_scale_f32 v46, vcc, s45, v82, s45
	s_mov_b64 s[58:59], 0
	v_fma_f32 v47, -v44, v45, 1.0
	v_fmac_f32_e32 v45, v47, v45
	v_mul_f32_e32 v47, v46, v45
	v_fma_f32 v48, -v44, v47, v46
	v_fmac_f32_e32 v47, v48, v45
	v_fma_f32 v44, -v44, v47, v46
	v_div_fmas_f32 v44, v44, v45, v47
	v_div_fixup_f32 v44, v44, v82, s45
	v_cmp_lt_f32_e32 vcc, 0, v82
	s_nop 1
	v_cndmask_b32_e32 v33, 0, v44, vcc
	v_fmaak_f32 v44, v40, v33, 0x4b400000
	v_fmaak_f32 v45, v36, v33, 0x4b400000
	v_fmaak_f32 v46, v38, v33, 0x4b400000
	v_fmaak_f32 v47, v34, v33, 0x4b400000
	v_fmaak_f32 v48, v41, v33, 0x4b400000
	v_fmaak_f32 v49, v37, v33, 0x4b400000
	v_fmaak_f32 v50, v39, v33, 0x4b400000
	v_fmaak_f32 v33, v35, v33, 0x4b400000
	v_perm_b32 v44, v44, v45, s62
	v_perm_b32 v45, v46, v47, s62
	v_perm_b32 v46, v48, v49, s62
	v_perm_b32 v33, v50, v33, s62
	v_perm_b32 v44, v44, v45, s63
	v_perm_b32 v45, v46, v33, s63
	global_store_dwordx2 v[42:43], v[44:45], off

.LBB0_842:
	s_cmp_eq_u32 s72, 2
	s_mov_b64 s[56:57], -1
	s_cbranch_scc0 .LBB0_844
	s_ashr_i32 s31, s30, 31
	v_lshl_add_u64 v[42:43], s[30:31], 0, v[64:65]
	v_lshl_add_u64 v[42:43], v[42:43], 2, s[36:37]
	s_nop 0
	v_add_u32_e32 v44, s30, v74
	v_mov_b64_e32 v[42:43], s[50:51]
	v_mad_u64_u32 v[42:43], s[56:57], v44, s71, v[42:43]
	v_ashrrev_i32_e32 v45, 31, v44
	v_mov_b32_e32 v44, v43
	v_mad_u64_u32 v[44:45], s[56:57], v45, s71, v[44:45]
	v_mov_b32_e32 v43, v44
	s_ashr_i32 s39, s38, 31
	v_lshl_add_u64 v[42:43], v[42:43], 0, s[38:39]
	v_lshl_add_u64 v[42:43], v[42:43], 0, v[68:69]
	s_nop 0
	v_div_scale_f32 v44, s[56:57], v83, v83, s45
	v_rcp_f32_e32 v45, v44
	v_div_scale_f32 v46, vcc, s45, v83, s45
	s_mov_b64 s[56:57], 0
	v_fma_f32 v47, -v44, v45, 1.0
	v_fmac_f32_e32 v45, v47, v45
	v_mul_f32_e32 v47, v46, v45
	v_fma_f32 v48, -v44, v47, v46
	v_fmac_f32_e32 v47, v48, v45
	v_fma_f32 v44, -v44, v47, v46
	v_div_fmas_f32 v44, v44, v45, v47
	v_div_fixup_f32 v44, v44, v83, s45
	v_cmp_lt_f32_e32 vcc, 0, v83
	s_nop 1
	v_cndmask_b32_e32 v33, 0, v44, vcc
	v_fmaak_f32 v44, v40, v33, 0x4b400000
	v_fmaak_f32 v45, v36, v33, 0x4b400000
	v_fmaak_f32 v46, v38, v33, 0x4b400000
	v_fmaak_f32 v47, v34, v33, 0x4b400000
	v_fmaak_f32 v48, v41, v33, 0x4b400000
	v_fmaak_f32 v49, v37, v33, 0x4b400000
	v_fmaak_f32 v50, v39, v33, 0x4b400000
	v_fmaak_f32 v33, v35, v33, 0x4b400000
	v_perm_b32 v44, v44, v45, s62
	v_perm_b32 v45, v46, v47, s62
	v_perm_b32 v46, v48, v49, s62
	v_perm_b32 v33, v50, v33, s62
	v_perm_b32 v44, v44, v45, s63
	v_perm_b32 v45, v46, v33, s63
	global_store_dwordx2 v[42:43], v[44:45], off

.LBB0_850:
	s_waitcnt lgkmcnt(0)
	s_andn2_b64 vcc, exec, s[54:55]
	s_mov_b64 s[12:13], -1
	s_cbranch_vccnz .LBB0_786
	s_add_i32 s3, s3, s2
	s_add_i32 s34, s34, s35
	s_mov_b64 s[12:13], 0
	s_waitcnt vmcnt(4)
	v_mov_b32_e32 v80, v84
	v_mov_b32_e32 v81, v85
	v_mov_b32_e32 v82, v86
	v_mov_b32_e32 v83, v87
	v_mov_b32_e32 v35, v27
	v_mov_b32_e32 v34, v26
	s_waitcnt lgkmcnt(0)
	v_mov_b32_e32 v33, v25
	v_mov_b32_e32 v32, v24
	v_mov_b32_e32 v39, v31
	v_mov_b32_e32 v38, v30
	v_mov_b32_e32 v37, v29
	v_mov_b32_e32 v36, v28
	v_mov_b32_e32 v43, v19
	v_mov_b32_e32 v42, v18
	v_mov_b32_e32 v41, v17
	v_mov_b32_e32 v40, v16
	v_mov_b32_e32 v47, v23
	v_mov_b32_e32 v46, v22
	v_mov_b32_e32 v45, v21
	v_mov_b32_e32 v44, v20
	v_mov_b32_e32 v51, v11
	v_mov_b32_e32 v50, v10
	v_mov_b32_e32 v49, v9
	v_mov_b32_e32 v48, v8
	v_mov_b32_e32 v55, v15
	v_mov_b32_e32 v54, v14
	v_mov_b32_e32 v53, v13
	v_mov_b32_e32 v52, v12
	v_mov_b32_e32 v59, v3
	v_mov_b32_e32 v58, v2
	v_mov_b32_e32 v57, v1
	v_mov_b32_e32 v56, v0
	v_mov_b32_e32 v63, v7
	v_mov_b32_e32 v62, v6
	v_mov_b32_e32 v61, v5
	v_mov_b32_e32 v60, v4
	s_branch .LBB0_786
